# GEMM mainloop: s_setprio moved across barriers, mid-phase setprio pair and redundant lgkmcnt(0) removed from the MFMA-phase critical path
# speedup vs baseline: 1.0049x; 1.0049x over previous
; #define PG8_STAGE(bufoff, gbase, voff) do { _Pragma("unroll") for (int _i = 0; _i < 2; ++_i) \
;         __builtin_amdgcn_global_load_lds((const unsigned*)((const char*)(gbase) + (voff)[_i]), (LAS unsigned*)(lds + (bufoff) + ldsw + _i * 8192), 16, 0, 0); } while (0)
; #define PG8_LDA(dst, b, h) do { _Pragma("unroll") for (int m = 0; m < 4; ++m) _Pragma("unroll") for (int k = 0; k < 2; ++k) dst[m][k] = *(const LAS bf16x8*)(lds + PG8_SA(b, h) + aoff + m * 2048 + k * 1024); } while (0)
; #define PG8_LDB(dst, b, h) do { _Pragma("unroll") for (int n = 0; n < 2; ++n) _Pragma("unroll") for (int k = 0; k < 2; ++k) dst[n][k] = *(const LAS bf16x8*)(lds + PG8_SB(b, h) + boff + n * 2048 + k * 1024); } while (0)
; #define PG8_MMA(ai, bj, At, Bt) do { __builtin_amdgcn_s_setprio(1); _Pragma("unroll") for (int m = 0; m < 4; ++m) _Pragma("unroll") for (int n = 0; n < 2; ++n) _Pragma("unroll") for (int k = 0; k < 2; ++k) \
;         acc[ai][bj][m][n] = __builtin_amdgcn_mfma_f32_16x16x32_bf16(Bt[n][k], At[m][k], acc[ai][bj][m][n], 0, 0, 0); __builtin_amdgcn_s_setprio(0); } while (0)
; #define PG8_WAIT_V(n) asm volatile("s_waitcnt vmcnt(" #n ")" ::: "memory")
; #define PG8_WAIT_L(n) asm volatile("s_waitcnt lgkmcnt(" #n ")" ::: "memory")
; #define PG8_BAR __builtin_amdgcn_s_barrier()
; #define PG8_SCHED __builtin_amdgcn_sched_barrier(0)
; template <class Epi>
; __device__ __forceinline__ void gemm_phase(LAS unsigned char* lds, const Gemm g, const StaticOrder& S, const Epi& E) {
;     ...
;             const bool last = (t == nt - 2);
;             const char* a1 = cA + (size_t)(t + 1) * kstep;
;             const char* a2 = last ? nA : cA + (size_t)(t + 2) * kstep; const char* b2 = last ? nB : cB + (size_t)(t + 2) * kstep;
;             const char* a3 = a2 + kstep; const char* b3 = b2 + kstep;
;             PG8_LDB(B0, 0, 0); PG8_LDB(B1, 0, 1); PG8_SCHED; PG8_LDA(At, 0, 0); PG8_STAGE(PG8_SA(1, 1), a1 + hstepA, voffA);
;             PG8_WAIT_V(8); PG8_WAIT_L(0); PG8_BAR; PG8_MMA(0, 0, At, B0); PG8_MMA(0, 1, At, B1); PG8_BAR; PG8_SCHED;
;             PG8_LDA(At, 0, 1); PG8_STAGE(PG8_SB(0, 0), b2, voffB); PG8_STAGE(PG8_SB(0, 1), b2 + hstepB, voffB); PG8_STAGE(PG8_SA(0, 0), a2, voffA);
;             PG8_WAIT_V(8); PG8_WAIT_L(0); PG8_BAR; PG8_MMA(1, 0, At, B0); PG8_MMA(1, 1, At, B1); PG8_BAR; PG8_SCHED;
.LBB0_233:
	s_add_i32 s83, s26, 2
	s_add_u32 vcc_lo, s12, 0x80
	s_addc_u32 s27, s13, 0
	s_add_i32 s52, 0, 0x10000
	s_cmp_eq_u32 s61, s26
	s_cselect_b32 s27, s3, s27
	s_cselect_b32 s26, s2, vcc_lo
	v_add_u32_e32 v155, s52, v145
	s_cselect_b32 vcc_hi, s25, s82
	s_cselect_b32 vcc_lo, s24, s57
	s_add_i32 s53, 0, 0x14000
	ds_read_b128 v[140:143], v155
	ds_read_b128 v[156:159], v155 offset:1024
	ds_read_b128 v[166:169], v155 offset:2048
	ds_read_b128 v[170:173], v155 offset:3072
	v_add_u32_e32 v155, s53, v145
	ds_read_b128 v[174:177], v155
	ds_read_b128 v[178:181], v155 offset:1024
	ds_read_b128 v[194:197], v155 offset:2048
	ds_read_b128 v[198:201], v155 offset:3072
	v_lshl_add_u64 v[160:161], s[12:13], 0, v[136:137]
	s_add_i32 m0, s30, 0xc000
	ds_read_b128 v[202:205], v154
	ds_read_b128 v[206:209], v154 offset:1024
	ds_read_b128 v[210:213], v154 offset:2048
	ds_read_b128 v[214:217], v154 offset:3072
	ds_read_b128 v[218:221], v154 offset:4096
	ds_read_b128 v[222:225], v154 offset:5120
	ds_read_b128 v[226:229], v154 offset:6144
	ds_read_b128 v[234:237], v154 offset:7168
	global_load_lds_dwordx4 v[160:161], off
	v_lshl_add_u64 v[160:161], s[12:13], 0, v[138:139]
	s_add_i32 m0, s30, 0xe000
	s_nop 0
	global_load_lds_dwordx4 v[160:161], off
	s_waitcnt vmcnt(8)
	s_waitcnt lgkmcnt(0)
	s_setprio 1
	s_barrier
	v_mfma_f32_16x16x32_bf16 v[126:129], v[140:143], v[202:205], v[126:129]
	v_mfma_f32_16x16x32_bf16 v[122:125], v[166:169], v[202:205], v[122:125]
	v_mfma_f32_16x16x32_bf16 v[110:113], v[140:143], v[210:213], v[110:113]
	v_mfma_f32_16x16x32_bf16 v[106:109], v[166:169], v[210:213], v[106:109]
	v_mfma_f32_16x16x32_bf16 v[94:97], v[140:143], v[218:221], v[94:97]
	v_mfma_f32_16x16x32_bf16 v[90:93], v[166:169], v[218:221], v[90:93]
	v_mfma_f32_16x16x32_bf16 v[78:81], v[140:143], v[226:229], v[78:81]
	v_mfma_f32_16x16x32_bf16 v[74:77], v[166:169], v[226:229], v[74:77]
	v_mfma_f32_16x16x32_bf16 v[126:129], v[156:159], v[206:209], v[126:129]
	v_mfma_f32_16x16x32_bf16 v[122:125], v[170:173], v[206:209], v[122:125]
	v_mfma_f32_16x16x32_bf16 v[110:113], v[156:159], v[214:217], v[110:113]
	v_mfma_f32_16x16x32_bf16 v[106:109], v[170:173], v[214:217], v[106:109]
	v_mfma_f32_16x16x32_bf16 v[94:97], v[156:159], v[222:225], v[94:97]
	v_mfma_f32_16x16x32_bf16 v[90:93], v[170:173], v[222:225], v[90:93]
	v_mfma_f32_16x16x32_bf16 v[78:81], v[156:159], v[234:237], v[78:81]
	v_mfma_f32_16x16x32_bf16 v[74:77], v[170:173], v[234:237], v[74:77]
	v_mfma_f32_16x16x32_bf16 v[118:121], v[174:177], v[202:205], v[118:121]
	v_mfma_f32_16x16x32_bf16 v[114:117], v[194:197], v[202:205], v[114:117]
	v_mfma_f32_16x16x32_bf16 v[102:105], v[174:177], v[210:213], v[102:105]
	v_mfma_f32_16x16x32_bf16 v[98:101], v[194:197], v[210:213], v[98:101]
	v_mfma_f32_16x16x32_bf16 v[86:89], v[174:177], v[218:221], v[86:89]
	v_mfma_f32_16x16x32_bf16 v[82:85], v[194:197], v[218:221], v[82:85]
	v_mfma_f32_16x16x32_bf16 v[70:73], v[174:177], v[226:229], v[70:73]
	v_mfma_f32_16x16x32_bf16 v[66:69], v[194:197], v[226:229], v[66:69]
	v_mfma_f32_16x16x32_bf16 v[118:121], v[178:181], v[206:209], v[118:121]
	v_mfma_f32_16x16x32_bf16 v[114:117], v[198:201], v[206:209], v[114:117]
	v_mfma_f32_16x16x32_bf16 v[102:105], v[178:181], v[214:217], v[102:105]
	v_mfma_f32_16x16x32_bf16 v[98:101], v[198:201], v[214:217], v[98:101]
	v_mfma_f32_16x16x32_bf16 v[86:89], v[178:181], v[222:225], v[86:89]
	v_mfma_f32_16x16x32_bf16 v[82:85], v[198:201], v[222:225], v[82:85]
	v_mfma_f32_16x16x32_bf16 v[70:73], v[178:181], v[234:237], v[70:73]
	v_mfma_f32_16x16x32_bf16 v[66:69], v[198:201], v[234:237], v[66:69]
	s_barrier
	s_setprio 0
	s_add_i32 s52, s52, s41
	v_lshl_add_u64 v[160:161], vcc, 0, v[0:1]
	s_mov_b32 m0, s52
	ds_read_b128 v[202:205], v154 offset:16384
	ds_read_b128 v[206:209], v154 offset:17408
	ds_read_b128 v[210:213], v154 offset:18432
	ds_read_b128 v[214:217], v154 offset:19456
	ds_read_b128 v[218:221], v154 offset:20480
	ds_read_b128 v[222:225], v154 offset:21504
	ds_read_b128 v[226:229], v154 offset:22528
	ds_read_b128 v[234:237], v154 offset:23552
	global_load_lds_dwordx4 v[160:161], off
	s_add_i32 m0, s52, 0x2000
	v_lshl_add_u64 v[182:183], vcc, 0, v[134:135]
	s_add_u32 vcc_lo, vcc_lo, s23
	s_addc_u32 vcc_hi, vcc_hi, 0
	s_add_i32 s52, s53, s41
	global_load_lds_dwordx4 v[182:183], off
	v_lshl_add_u64 v[238:239], vcc, 0, v[0:1]
	s_mov_b32 m0, s52
	v_lshl_add_u64 v[240:241], vcc, 0, v[134:135]
	global_load_lds_dwordx4 v[238:239], off
	s_add_i32 m0, s52, 0x2000
	v_lshl_add_u64 v[242:243], s[26:27], 0, v[130:131]
	global_load_lds_dwordx4 v[240:241], off
	s_mov_b32 m0, s30
	v_lshl_add_u64 v[244:245], s[26:27], 0, v[132:133]
	global_load_lds_dwordx4 v[242:243], off
	s_mov_b32 m0, s31
	s_nop 0
	global_load_lds_dwordx4 v[244:245], off
	s_waitcnt vmcnt(8)
	s_waitcnt lgkmcnt(0)
	s_setprio 1
	s_barrier
; #define PG8_STAGE(bufoff, gbase, voff) do { _Pragma("unroll") for (int _i = 0; _i < 2; ++_i) \
;         __builtin_amdgcn_global_load_lds((const unsigned*)((const char*)(gbase) + (voff)[_i]), (LAS unsigned*)(lds + (bufoff) + ldsw + _i * 8192), 16, 0, 0); } while (0)
; #define PG8_LDA(dst, b, h) do { _Pragma("unroll") for (int m = 0; m < 4; ++m) _Pragma("unroll") for (int k = 0; k < 2; ++k) dst[m][k] = *(const LAS bf16x8*)(lds + PG8_SA(b, h) + aoff + m * 2048 + k * 1024); } while (0)
; #define PG8_LDB(dst, b, h) do { _Pragma("unroll") for (int n = 0; n < 2; ++n) _Pragma("unroll") for (int k = 0; k < 2; ++k) dst[n][k] = *(const LAS bf16x8*)(lds + PG8_SB(b, h) + boff + n * 2048 + k * 1024); } while (0)
; #define PG8_MMA(ai, bj, At, Bt) do { __builtin_amdgcn_s_setprio(1); _Pragma("unroll") for (int m = 0; m < 4; ++m) _Pragma("unroll") for (int n = 0; n < 2; ++n) _Pragma("unroll") for (int k = 0; k < 2; ++k) \
;         acc[ai][bj][m][n] = __builtin_amdgcn_mfma_f32_16x16x32_bf16(Bt[n][k], At[m][k], acc[ai][bj][m][n], 0, 0, 0); __builtin_amdgcn_s_setprio(0); } while (0)
; #define PG8_WAIT_V(n) asm volatile("s_waitcnt vmcnt(" #n ")" ::: "memory")
; #define PG8_WAIT_L(n) asm volatile("s_waitcnt lgkmcnt(" #n ")" ::: "memory")
; #define PG8_BAR __builtin_amdgcn_s_barrier()
; #define PG8_SCHED __builtin_amdgcn_sched_barrier(0)
; template <class Epi>
; __device__ __forceinline__ void gemm_phase(LAS unsigned char* lds, const Gemm g, const StaticOrder& S, const Epi& E) {
;     ...
;             PG8_WAIT_V(8); PG8_WAIT_L(0); PG8_BAR; PG8_MMA(1, 0, At, B0); PG8_MMA(1, 1, At, B1); PG8_BAR; PG8_SCHED;
;             PG8_LDB(B0, 1, 0); PG8_LDB(B1, 1, 1); PG8_SCHED; PG8_LDA(At, 1, 0); PG8_STAGE(PG8_SA(0, 1), a2 + hstepA, voffA);
;             PG8_WAIT_V(8); PG8_WAIT_L(0); PG8_BAR; PG8_MMA(0, 0, At, B0); PG8_MMA(0, 1, At, B1); PG8_BAR; PG8_SCHED;
	v_mfma_f32_16x16x32_bf16 v[62:65], v[140:143], v[202:205], v[62:65]
	v_mfma_f32_16x16x32_bf16 v[58:61], v[166:169], v[202:205], v[58:61]
	v_mfma_f32_16x16x32_bf16 v[46:49], v[140:143], v[210:213], v[46:49]
	v_mfma_f32_16x16x32_bf16 v[42:45], v[166:169], v[210:213], v[42:45]
	v_mfma_f32_16x16x32_bf16 v[30:33], v[140:143], v[218:221], v[30:33]
	v_mfma_f32_16x16x32_bf16 v[26:29], v[166:169], v[218:221], v[26:29]
	v_mfma_f32_16x16x32_bf16 v[14:17], v[140:143], v[226:229], v[14:17]
	v_mfma_f32_16x16x32_bf16 v[10:13], v[166:169], v[226:229], v[10:13]
	v_mfma_f32_16x16x32_bf16 v[62:65], v[156:159], v[206:209], v[62:65]
	v_mfma_f32_16x16x32_bf16 v[58:61], v[170:173], v[206:209], v[58:61]
	v_mfma_f32_16x16x32_bf16 v[46:49], v[156:159], v[214:217], v[46:49]
	v_mfma_f32_16x16x32_bf16 v[42:45], v[170:173], v[214:217], v[42:45]
	v_mfma_f32_16x16x32_bf16 v[30:33], v[156:159], v[222:225], v[30:33]
	v_mfma_f32_16x16x32_bf16 v[26:29], v[170:173], v[222:225], v[26:29]
	v_mfma_f32_16x16x32_bf16 v[14:17], v[156:159], v[234:237], v[14:17]
	v_mfma_f32_16x16x32_bf16 v[10:13], v[170:173], v[234:237], v[10:13]
	v_mfma_f32_16x16x32_bf16 v[54:57], v[174:177], v[202:205], v[54:57]
	v_mfma_f32_16x16x32_bf16 v[50:53], v[194:197], v[202:205], v[50:53]
	v_mfma_f32_16x16x32_bf16 v[38:41], v[174:177], v[210:213], v[38:41]
	v_mfma_f32_16x16x32_bf16 v[34:37], v[194:197], v[210:213], v[34:37]
	v_mfma_f32_16x16x32_bf16 v[22:25], v[174:177], v[218:221], v[22:25]
	v_mfma_f32_16x16x32_bf16 v[18:21], v[194:197], v[218:221], v[18:21]
	v_mfma_f32_16x16x32_bf16 v[6:9], v[174:177], v[226:229], v[6:9]
	v_mfma_f32_16x16x32_bf16 v[2:5], v[194:197], v[226:229], v[2:5]
	v_mfma_f32_16x16x32_bf16 v[54:57], v[178:181], v[206:209], v[54:57]
	v_mfma_f32_16x16x32_bf16 v[50:53], v[198:201], v[206:209], v[50:53]
	v_mfma_f32_16x16x32_bf16 v[38:41], v[178:181], v[214:217], v[38:41]
	v_mfma_f32_16x16x32_bf16 v[34:37], v[198:201], v[214:217], v[34:37]
	v_mfma_f32_16x16x32_bf16 v[22:25], v[178:181], v[222:225], v[22:25]
	v_mfma_f32_16x16x32_bf16 v[18:21], v[198:201], v[222:225], v[18:21]
	v_mfma_f32_16x16x32_bf16 v[6:9], v[178:181], v[234:237], v[6:9]
	v_mfma_f32_16x16x32_bf16 v[2:5], v[198:201], v[234:237], v[2:5]
	s_barrier
	s_setprio 0
	s_add_i32 s52, 0, 0x18000
	v_add_u32_e32 v155, s52, v145
	s_add_i32 s53, 0, 0x1c000
	ds_read_b128 v[140:143], v155
	ds_read_b128 v[156:159], v155 offset:1024
	ds_read_b128 v[166:169], v155 offset:2048
	ds_read_b128 v[170:173], v155 offset:3072
	v_add_u32_e32 v155, s53, v145
	ds_read_b128 v[174:177], v155
	ds_read_b128 v[178:181], v155 offset:1024
	ds_read_b128 v[194:197], v155 offset:2048
	ds_read_b128 v[198:201], v155 offset:3072
	s_add_u32 s26, s26, s78
	s_addc_u32 s27, s27, 0
	s_mov_b32 m0, s64
	v_lshl_add_u64 v[246:247], s[26:27], 0, v[130:131]
	ds_read_b128 v[202:205], v154 offset:32768
	ds_read_b128 v[206:209], v154 offset:33792
	ds_read_b128 v[210:213], v154 offset:34816
	ds_read_b128 v[214:217], v154 offset:35840
	ds_read_b128 v[218:221], v154 offset:36864
	ds_read_b128 v[222:225], v154 offset:37888
	ds_read_b128 v[226:229], v154 offset:38912
	ds_read_b128 v[234:237], v154 offset:39936
	global_load_lds_dwordx4 v[246:247], off
	v_lshl_add_u64 v[246:247], s[26:27], 0, v[132:133]
	s_mov_b32 m0, s85
	s_nop 0
	global_load_lds_dwordx4 v[246:247], off
	s_waitcnt vmcnt(8)
	s_waitcnt lgkmcnt(0)
	s_setprio 1
	s_barrier
	v_mfma_f32_16x16x32_bf16 v[126:129], v[140:143], v[202:205], v[126:129]
	v_mfma_f32_16x16x32_bf16 v[122:125], v[166:169], v[202:205], v[122:125]
	v_mfma_f32_16x16x32_bf16 v[110:113], v[140:143], v[210:213], v[110:113]
	v_mfma_f32_16x16x32_bf16 v[106:109], v[166:169], v[210:213], v[106:109]
	v_mfma_f32_16x16x32_bf16 v[94:97], v[140:143], v[218:221], v[94:97]
	v_mfma_f32_16x16x32_bf16 v[90:93], v[166:169], v[218:221], v[90:93]
	v_mfma_f32_16x16x32_bf16 v[78:81], v[140:143], v[226:229], v[78:81]
	v_mfma_f32_16x16x32_bf16 v[74:77], v[166:169], v[226:229], v[74:77]
	v_mfma_f32_16x16x32_bf16 v[126:129], v[156:159], v[206:209], v[126:129]
	v_mfma_f32_16x16x32_bf16 v[122:125], v[170:173], v[206:209], v[122:125]
	v_mfma_f32_16x16x32_bf16 v[110:113], v[156:159], v[214:217], v[110:113]
	v_mfma_f32_16x16x32_bf16 v[106:109], v[170:173], v[214:217], v[106:109]
	v_mfma_f32_16x16x32_bf16 v[94:97], v[156:159], v[222:225], v[94:97]
	v_mfma_f32_16x16x32_bf16 v[90:93], v[170:173], v[222:225], v[90:93]
	v_mfma_f32_16x16x32_bf16 v[78:81], v[156:159], v[234:237], v[78:81]
	v_mfma_f32_16x16x32_bf16 v[74:77], v[170:173], v[234:237], v[74:77]
	v_mfma_f32_16x16x32_bf16 v[118:121], v[174:177], v[202:205], v[118:121]
	v_mfma_f32_16x16x32_bf16 v[114:117], v[194:197], v[202:205], v[114:117]
	v_mfma_f32_16x16x32_bf16 v[102:105], v[174:177], v[210:213], v[102:105]
	v_mfma_f32_16x16x32_bf16 v[98:101], v[194:197], v[210:213], v[98:101]
	v_mfma_f32_16x16x32_bf16 v[86:89], v[174:177], v[218:221], v[86:89]
	v_mfma_f32_16x16x32_bf16 v[82:85], v[194:197], v[218:221], v[82:85]
	v_mfma_f32_16x16x32_bf16 v[70:73], v[174:177], v[226:229], v[70:73]
	v_mfma_f32_16x16x32_bf16 v[66:69], v[194:197], v[226:229], v[66:69]
	v_mfma_f32_16x16x32_bf16 v[118:121], v[178:181], v[206:209], v[118:121]
	v_mfma_f32_16x16x32_bf16 v[114:117], v[198:201], v[206:209], v[114:117]
	v_mfma_f32_16x16x32_bf16 v[102:105], v[178:181], v[214:217], v[102:105]
	v_mfma_f32_16x16x32_bf16 v[98:101], v[198:201], v[214:217], v[98:101]
	v_mfma_f32_16x16x32_bf16 v[86:89], v[178:181], v[222:225], v[86:89]
	v_mfma_f32_16x16x32_bf16 v[82:85], v[198:201], v[222:225], v[82:85]
	v_mfma_f32_16x16x32_bf16 v[70:73], v[178:181], v[234:237], v[70:73]
	v_mfma_f32_16x16x32_bf16 v[66:69], v[198:201], v[234:237], v[66:69]
	s_barrier
; #define PG8_STAGE(bufoff, gbase, voff) do { _Pragma("unroll") for (int _i = 0; _i < 2; ++_i) \
;         __builtin_amdgcn_global_load_lds((const unsigned*)((const char*)(gbase) + (voff)[_i]), (LAS unsigned*)(lds + (bufoff) + ldsw + _i * 8192), 16, 0, 0); } while (0)
; #define PG8_LDA(dst, b, h) do { _Pragma("unroll") for (int m = 0; m < 4; ++m) _Pragma("unroll") for (int k = 0; k < 2; ++k) dst[m][k] = *(const LAS bf16x8*)(lds + PG8_SA(b, h) + aoff + m * 2048 + k * 1024); } while (0)
; #define PG8_MMA(ai, bj, At, Bt) do { __builtin_amdgcn_s_setprio(1); _Pragma("unroll") for (int m = 0; m < 4; ++m) _Pragma("unroll") for (int n = 0; n < 2; ++n) _Pragma("unroll") for (int k = 0; k < 2; ++k) \
;         acc[ai][bj][m][n] = __builtin_amdgcn_mfma_f32_16x16x32_bf16(Bt[n][k], At[m][k], acc[ai][bj][m][n], 0, 0, 0); __builtin_amdgcn_s_setprio(0); } while (0)
; #define PG8_WAIT_V(n) asm volatile("s_waitcnt vmcnt(" #n ")" ::: "memory")
; #define PG8_WAIT_L(n) asm volatile("s_waitcnt lgkmcnt(" #n ")" ::: "memory")
; #define PG8_BAR __builtin_amdgcn_s_barrier()
; #define PG8_SCHED __builtin_amdgcn_sched_barrier(0)
; template <class Epi>
; __device__ __forceinline__ void gemm_phase(LAS unsigned char* lds, const Gemm g, const StaticOrder& S, const Epi& E) {
;     ...
;             PG8_LDA(At, 1, 1); PG8_STAGE(PG8_SB(1, 0), b3, voffB); PG8_STAGE(PG8_SB(1, 1), b3 + hstepB, voffB); PG8_STAGE(PG8_SA(1, 0), a3, voffA);
;             PG8_WAIT_V(8); PG8_WAIT_L(0); PG8_BAR; PG8_MMA(1, 0, At, B0); PG8_MMA(1, 1, At, B1); PG8_BAR; PG8_SCHED;
;         }
;         if (wr == 0) PG8_BAR;
	s_setprio 0
	s_add_i32 s26, s52, s41
	v_lshl_add_u64 v[160:161], v[160:161], 0, s[76:77]
	s_mov_b32 m0, s26
	ds_read_b128 v[202:205], v154 offset:49152
	ds_read_b128 v[206:209], v154 offset:50176
	ds_read_b128 v[210:213], v154 offset:51200
	ds_read_b128 v[214:217], v154 offset:52224
	ds_read_b128 v[218:221], v154 offset:53248
	ds_read_b128 v[222:225], v154 offset:54272
	ds_read_b128 v[226:229], v154 offset:55296
	ds_read_b128 v[234:237], v154 offset:56320
	global_load_lds_dwordx4 v[160:161], off
	v_lshl_add_u64 v[160:161], v[182:183], 0, s[76:77]
	s_add_i32 m0, s26, 0x2000
	s_add_i32 s26, s53, s41
	global_load_lds_dwordx4 v[160:161], off
	v_lshl_add_u64 v[160:161], v[238:239], 0, s[76:77]
	s_mov_b32 m0, s26
	s_nop 0
	global_load_lds_dwordx4 v[160:161], off
	v_lshl_add_u64 v[160:161], v[240:241], 0, s[76:77]
	s_add_i32 m0, s26, 0x2000
	s_nop 0
	global_load_lds_dwordx4 v[160:161], off
	v_lshl_add_u64 v[160:161], v[242:243], 0, s[76:77]
	s_mov_b32 m0, s92
	s_nop 0
	global_load_lds_dwordx4 v[160:161], off
	v_lshl_add_u64 v[160:161], v[244:245], 0, s[76:77]
	s_mov_b32 m0, s93
	s_nop 0
	global_load_lds_dwordx4 v[160:161], off
	s_waitcnt vmcnt(8)
	s_waitcnt lgkmcnt(0)
	s_setprio 1
	s_barrier
	v_mfma_f32_16x16x32_bf16 v[62:65], v[140:143], v[202:205], v[62:65]
	v_mfma_f32_16x16x32_bf16 v[58:61], v[166:169], v[202:205], v[58:61]
	v_mfma_f32_16x16x32_bf16 v[46:49], v[140:143], v[210:213], v[46:49]
	v_mfma_f32_16x16x32_bf16 v[42:45], v[166:169], v[210:213], v[42:45]
	v_mfma_f32_16x16x32_bf16 v[30:33], v[140:143], v[218:221], v[30:33]
	v_mfma_f32_16x16x32_bf16 v[26:29], v[166:169], v[218:221], v[26:29]
	v_mfma_f32_16x16x32_bf16 v[14:17], v[140:143], v[226:229], v[14:17]
	v_mfma_f32_16x16x32_bf16 v[10:13], v[166:169], v[226:229], v[10:13]
	v_mfma_f32_16x16x32_bf16 v[62:65], v[156:159], v[206:209], v[62:65]
	v_mfma_f32_16x16x32_bf16 v[58:61], v[170:173], v[206:209], v[58:61]
	v_mfma_f32_16x16x32_bf16 v[46:49], v[156:159], v[214:217], v[46:49]
	v_mfma_f32_16x16x32_bf16 v[42:45], v[170:173], v[214:217], v[42:45]
	v_mfma_f32_16x16x32_bf16 v[30:33], v[156:159], v[222:225], v[30:33]
	v_mfma_f32_16x16x32_bf16 v[26:29], v[170:173], v[222:225], v[26:29]
	v_mfma_f32_16x16x32_bf16 v[14:17], v[156:159], v[234:237], v[14:17]
	v_mfma_f32_16x16x32_bf16 v[10:13], v[170:173], v[234:237], v[10:13]
	v_mfma_f32_16x16x32_bf16 v[54:57], v[174:177], v[202:205], v[54:57]
	v_mfma_f32_16x16x32_bf16 v[50:53], v[194:197], v[202:205], v[50:53]
	v_mfma_f32_16x16x32_bf16 v[38:41], v[174:177], v[210:213], v[38:41]
	v_mfma_f32_16x16x32_bf16 v[34:37], v[194:197], v[210:213], v[34:37]
	v_mfma_f32_16x16x32_bf16 v[22:25], v[174:177], v[218:221], v[22:25]
	v_mfma_f32_16x16x32_bf16 v[18:21], v[194:197], v[218:221], v[18:21]
	v_mfma_f32_16x16x32_bf16 v[6:9], v[174:177], v[226:229], v[6:9]
	v_mfma_f32_16x16x32_bf16 v[2:5], v[194:197], v[226:229], v[2:5]
	v_mfma_f32_16x16x32_bf16 v[54:57], v[178:181], v[206:209], v[54:57]
	v_mfma_f32_16x16x32_bf16 v[50:53], v[198:201], v[206:209], v[50:53]
	v_mfma_f32_16x16x32_bf16 v[38:41], v[178:181], v[214:217], v[38:41]
	v_mfma_f32_16x16x32_bf16 v[34:37], v[198:201], v[214:217], v[34:37]
	v_mfma_f32_16x16x32_bf16 v[22:25], v[178:181], v[222:225], v[22:25]
	v_mfma_f32_16x16x32_bf16 v[18:21], v[198:201], v[222:225], v[18:21]
	v_mfma_f32_16x16x32_bf16 v[6:9], v[178:181], v[234:237], v[6:9]
	v_mfma_f32_16x16x32_bf16 v[2:5], v[198:201], v[234:237], v[2:5]
	s_barrier
	s_setprio 0
	s_add_u32 s12, s12, 0x100
	s_addc_u32 s13, s13, 0
	s_add_u32 s57, s57, 0x100
	s_addc_u32 s82, s82, 0
	s_cmp_ge_u32 s83, s80
	s_mov_b32 s26, s83
	s_cbranch_scc0 .LBB0_233
	s_and_b64 vcc, exec, s[74:75]
	s_cbranch_vccz .LBB0_236
	s_barrier

; #define PG8_STAGE(bufoff, gbase, voff) do { _Pragma("unroll") for (int _i = 0; _i < 2; ++_i) \
;         __builtin_amdgcn_global_load_lds((const unsigned*)((const char*)(gbase) + (voff)[_i]), (LAS unsigned*)(lds + (bufoff) + ldsw + _i * 8192), 16, 0, 0); } while (0)
; #define PG8_LDA(dst, b, h) do { _Pragma("unroll") for (int m = 0; m < 4; ++m) _Pragma("unroll") for (int k = 0; k < 2; ++k) dst[m][k] = *(const LAS bf16x8*)(lds + PG8_SA(b, h) + aoff + m * 2048 + k * 1024); } while (0)
; #define PG8_LDB(dst, b, h) do { _Pragma("unroll") for (int n = 0; n < 2; ++n) _Pragma("unroll") for (int k = 0; k < 2; ++k) dst[n][k] = *(const LAS bf16x8*)(lds + PG8_SB(b, h) + boff + n * 2048 + k * 1024); } while (0)
; #define PG8_MMA(ai, bj, At, Bt) do { __builtin_amdgcn_s_setprio(1); _Pragma("unroll") for (int m = 0; m < 4; ++m) _Pragma("unroll") for (int n = 0; n < 2; ++n) _Pragma("unroll") for (int k = 0; k < 2; ++k) \
;         acc[ai][bj][m][n] = __builtin_amdgcn_mfma_f32_16x16x32_bf16(Bt[n][k], At[m][k], acc[ai][bj][m][n], 0, 0, 0); __builtin_amdgcn_s_setprio(0); } while (0)
; #define PG8_WAIT_V(n) asm volatile("s_waitcnt vmcnt(" #n ")" ::: "memory")
; #define PG8_WAIT_L(n) asm volatile("s_waitcnt lgkmcnt(" #n ")" ::: "memory")
; #define PG8_BAR __builtin_amdgcn_s_barrier()
; #define PG8_SCHED __builtin_amdgcn_sched_barrier(0)
; template <class Epi>
; __device__ __forceinline__ void gemm_phase(LAS unsigned char* lds, const Gemm g, const StaticOrder& S, const Epi& E) {
;     ...
;             const bool last = (t == nt - 2);
;             const char* a1 = cA + (size_t)(t + 1) * kstep;
;             const char* a2 = last ? nA : cA + (size_t)(t + 2) * kstep; const char* b2 = last ? nB : cB + (size_t)(t + 2) * kstep;
;             const char* a3 = a2 + kstep; const char* b3 = b2 + kstep;
;             PG8_LDB(B0, 0, 0); PG8_LDB(B1, 0, 1); PG8_SCHED; PG8_LDA(At, 0, 0); PG8_STAGE(PG8_SA(1, 1), a1 + hstepA, voffA);
;             PG8_WAIT_V(8); PG8_WAIT_L(0); PG8_BAR; PG8_MMA(0, 0, At, B0); PG8_MMA(0, 1, At, B1); PG8_BAR; PG8_SCHED;
;             PG8_LDA(At, 0, 1); PG8_STAGE(PG8_SB(0, 0), b2, voffB); PG8_STAGE(PG8_SB(0, 1), b2 + hstepB, voffB); PG8_STAGE(PG8_SA(0, 0), a2, voffA);
;             PG8_WAIT_V(8); PG8_WAIT_L(0); PG8_BAR; PG8_MMA(1, 0, At, B0); PG8_MMA(1, 1, At, B1); PG8_BAR; PG8_SCHED;
.LBB0_295:
	s_add_u32 s26, s24, 0xfff80080
	s_addc_u32 s27, s25, -1
	s_add_i32 s50, 0, 0x10000
	s_cmp_eq_u32 s49, 28
	s_cselect_b32 s35, s13, s27
	s_cselect_b32 s34, s43, s26
	s_cselect_b32 s27, s11, s48
	s_cselect_b32 s26, s46, s47
	s_add_i32 s56, 0, 0x14000
	v_add_u32_e32 v156, s50, v145
	v_add_u32_e32 v160, s56, v145
	ds_read_b128 v[140:143], v156
	ds_read_b128 v[148:151], v156 offset:1024
	ds_read_b128 v[152:155], v156 offset:2048
	ds_read_b128 v[156:159], v156 offset:3072
	ds_read_b128 v[166:169], v160
	ds_read_b128 v[170:173], v160 offset:1024
	ds_read_b128 v[174:177], v160 offset:2048
	ds_read_b128 v[178:181], v160 offset:3072
	v_lshl_add_u64 v[160:161], s[24:25], 0, v[136:137]
	s_add_i32 m0, s19, 0xc000
	ds_read_b128 v[194:197], v147
	ds_read_b128 v[198:201], v147 offset:1024
	ds_read_b128 v[202:205], v147 offset:2048
	ds_read_b128 v[206:209], v147 offset:3072
	ds_read_b128 v[210:213], v147 offset:4096
	ds_read_b128 v[214:217], v147 offset:5120
	ds_read_b128 v[218:221], v147 offset:6144
	ds_read_b128 v[222:225], v147 offset:7168
	global_load_lds_dwordx4 v[160:161], off
	v_lshl_add_u64 v[160:161], s[24:25], 0, v[138:139]
	s_add_i32 m0, s19, 0xe000
	s_nop 0
	global_load_lds_dwordx4 v[160:161], off
	s_waitcnt vmcnt(8)
	s_waitcnt lgkmcnt(0)
	s_setprio 1
	s_barrier
	v_mfma_f32_16x16x32_bf16 v[126:129], v[140:143], v[194:197], v[126:129]
	v_mfma_f32_16x16x32_bf16 v[122:125], v[152:155], v[194:197], v[122:125]
	v_mfma_f32_16x16x32_bf16 v[110:113], v[140:143], v[202:205], v[110:113]
	v_mfma_f32_16x16x32_bf16 v[106:109], v[152:155], v[202:205], v[106:109]
	v_mfma_f32_16x16x32_bf16 v[94:97], v[140:143], v[210:213], v[94:97]
	v_mfma_f32_16x16x32_bf16 v[90:93], v[152:155], v[210:213], v[90:93]
	v_mfma_f32_16x16x32_bf16 v[78:81], v[140:143], v[218:221], v[78:81]
	v_mfma_f32_16x16x32_bf16 v[74:77], v[152:155], v[218:221], v[74:77]
	v_mfma_f32_16x16x32_bf16 v[126:129], v[148:151], v[198:201], v[126:129]
	v_mfma_f32_16x16x32_bf16 v[122:125], v[156:159], v[198:201], v[122:125]
	v_mfma_f32_16x16x32_bf16 v[110:113], v[148:151], v[206:209], v[110:113]
	v_mfma_f32_16x16x32_bf16 v[106:109], v[156:159], v[206:209], v[106:109]
	v_mfma_f32_16x16x32_bf16 v[94:97], v[148:151], v[214:217], v[94:97]
	v_mfma_f32_16x16x32_bf16 v[90:93], v[156:159], v[214:217], v[90:93]
	v_mfma_f32_16x16x32_bf16 v[78:81], v[148:151], v[222:225], v[78:81]
	v_mfma_f32_16x16x32_bf16 v[74:77], v[156:159], v[222:225], v[74:77]
	v_mfma_f32_16x16x32_bf16 v[118:121], v[166:169], v[194:197], v[118:121]
	v_mfma_f32_16x16x32_bf16 v[114:117], v[174:177], v[194:197], v[114:117]
	v_mfma_f32_16x16x32_bf16 v[102:105], v[166:169], v[202:205], v[102:105]
	v_mfma_f32_16x16x32_bf16 v[98:101], v[174:177], v[202:205], v[98:101]
	v_mfma_f32_16x16x32_bf16 v[86:89], v[166:169], v[210:213], v[86:89]
	v_mfma_f32_16x16x32_bf16 v[82:85], v[174:177], v[210:213], v[82:85]
	v_mfma_f32_16x16x32_bf16 v[70:73], v[166:169], v[218:221], v[70:73]
	v_mfma_f32_16x16x32_bf16 v[66:69], v[174:177], v[218:221], v[66:69]
	v_mfma_f32_16x16x32_bf16 v[118:121], v[170:173], v[198:201], v[118:121]
	v_mfma_f32_16x16x32_bf16 v[114:117], v[178:181], v[198:201], v[114:117]
	v_mfma_f32_16x16x32_bf16 v[102:105], v[170:173], v[206:209], v[102:105]
	v_mfma_f32_16x16x32_bf16 v[98:101], v[178:181], v[206:209], v[98:101]
	v_mfma_f32_16x16x32_bf16 v[86:89], v[170:173], v[214:217], v[86:89]
	v_mfma_f32_16x16x32_bf16 v[82:85], v[178:181], v[214:217], v[82:85]
	v_mfma_f32_16x16x32_bf16 v[70:73], v[170:173], v[222:225], v[70:73]
	v_mfma_f32_16x16x32_bf16 v[66:69], v[178:181], v[222:225], v[66:69]
	s_barrier
	s_setprio 0
	s_add_i32 s50, s50, s23
	v_lshl_add_u64 v[160:161], s[26:27], 0, v[0:1]
	s_mov_b32 m0, s50
	ds_read_b128 v[194:197], v147 offset:16384
	ds_read_b128 v[198:201], v147 offset:17408
	ds_read_b128 v[202:205], v147 offset:18432
	ds_read_b128 v[206:209], v147 offset:19456
	ds_read_b128 v[210:213], v147 offset:20480
	ds_read_b128 v[214:217], v147 offset:21504
	ds_read_b128 v[218:221], v147 offset:22528
	ds_read_b128 v[222:225], v147 offset:23552
	global_load_lds_dwordx4 v[160:161], off
	s_add_i32 m0, s50, 0x2000
	s_add_u32 s50, s26, 0x80000
	v_lshl_add_u64 v[182:183], s[26:27], 0, v[130:131]
	s_addc_u32 s51, s27, 0
	s_add_i32 s56, s56, s23
	global_load_lds_dwordx4 v[182:183], off
	v_lshl_add_u64 v[226:227], s[50:51], 0, v[0:1]
	s_mov_b32 m0, s56
	v_lshl_add_u64 v[228:229], s[34:35], 0, v[132:133]
	global_load_lds_dwordx4 v[226:227], off
	v_lshl_add_u64 v[226:227], s[50:51], 0, v[130:131]
	s_add_i32 m0, s56, 0x2000
	s_nop 0
	global_load_lds_dwordx4 v[226:227], off
	v_lshl_add_u64 v[226:227], s[34:35], 0, v[134:135]
	s_mov_b32 m0, s19
	s_nop 0
	global_load_lds_dwordx4 v[226:227], off
	s_mov_b32 m0, s31
	s_nop 0
	global_load_lds_dwordx4 v[228:229], off
	s_waitcnt vmcnt(8)
	s_waitcnt lgkmcnt(0)
	s_setprio 1
	s_barrier
; #define PG8_STAGE(bufoff, gbase, voff) do { _Pragma("unroll") for (int _i = 0; _i < 2; ++_i) \
;         __builtin_amdgcn_global_load_lds((const unsigned*)((const char*)(gbase) + (voff)[_i]), (LAS unsigned*)(lds + (bufoff) + ldsw + _i * 8192), 16, 0, 0); } while (0)
; #define PG8_LDA(dst, b, h) do { _Pragma("unroll") for (int m = 0; m < 4; ++m) _Pragma("unroll") for (int k = 0; k < 2; ++k) dst[m][k] = *(const LAS bf16x8*)(lds + PG8_SA(b, h) + aoff + m * 2048 + k * 1024); } while (0)
; #define PG8_LDB(dst, b, h) do { _Pragma("unroll") for (int n = 0; n < 2; ++n) _Pragma("unroll") for (int k = 0; k < 2; ++k) dst[n][k] = *(const LAS bf16x8*)(lds + PG8_SB(b, h) + boff + n * 2048 + k * 1024); } while (0)
; #define PG8_MMA(ai, bj, At, Bt) do { __builtin_amdgcn_s_setprio(1); _Pragma("unroll") for (int m = 0; m < 4; ++m) _Pragma("unroll") for (int n = 0; n < 2; ++n) _Pragma("unroll") for (int k = 0; k < 2; ++k) \
;         acc[ai][bj][m][n] = __builtin_amdgcn_mfma_f32_16x16x32_bf16(Bt[n][k], At[m][k], acc[ai][bj][m][n], 0, 0, 0); __builtin_amdgcn_s_setprio(0); } while (0)
; #define PG8_WAIT_V(n) asm volatile("s_waitcnt vmcnt(" #n ")" ::: "memory")
; #define PG8_WAIT_L(n) asm volatile("s_waitcnt lgkmcnt(" #n ")" ::: "memory")
; #define PG8_BAR __builtin_amdgcn_s_barrier()
; #define PG8_SCHED __builtin_amdgcn_sched_barrier(0)
; template <class Epi>
; __device__ __forceinline__ void gemm_phase(LAS unsigned char* lds, const Gemm g, const StaticOrder& S, const Epi& E) {
;     ...
;             PG8_WAIT_V(8); PG8_WAIT_L(0); PG8_BAR; PG8_MMA(1, 0, At, B0); PG8_MMA(1, 1, At, B1); PG8_BAR; PG8_SCHED;
;             PG8_LDB(B0, 1, 0); PG8_LDB(B1, 1, 1); PG8_SCHED; PG8_LDA(At, 1, 0); PG8_STAGE(PG8_SA(0, 1), a2 + hstepA, voffA);
;             PG8_WAIT_V(8); PG8_WAIT_L(0); PG8_BAR; PG8_MMA(0, 0, At, B0); PG8_MMA(0, 1, At, B1); PG8_BAR; PG8_SCHED;
	v_mfma_f32_16x16x32_bf16 v[62:65], v[140:143], v[194:197], v[62:65]
	v_mfma_f32_16x16x32_bf16 v[58:61], v[152:155], v[194:197], v[58:61]
	v_mfma_f32_16x16x32_bf16 v[46:49], v[140:143], v[202:205], v[46:49]
	v_mfma_f32_16x16x32_bf16 v[42:45], v[152:155], v[202:205], v[42:45]
	v_mfma_f32_16x16x32_bf16 v[30:33], v[140:143], v[210:213], v[30:33]
	v_mfma_f32_16x16x32_bf16 v[26:29], v[152:155], v[210:213], v[26:29]
	v_mfma_f32_16x16x32_bf16 v[14:17], v[140:143], v[218:221], v[14:17]
	v_mfma_f32_16x16x32_bf16 v[10:13], v[152:155], v[218:221], v[10:13]
	v_mfma_f32_16x16x32_bf16 v[62:65], v[148:151], v[198:201], v[62:65]
	v_mfma_f32_16x16x32_bf16 v[58:61], v[156:159], v[198:201], v[58:61]
	v_mfma_f32_16x16x32_bf16 v[46:49], v[148:151], v[206:209], v[46:49]
	v_mfma_f32_16x16x32_bf16 v[42:45], v[156:159], v[206:209], v[42:45]
	v_mfma_f32_16x16x32_bf16 v[30:33], v[148:151], v[214:217], v[30:33]
	v_mfma_f32_16x16x32_bf16 v[26:29], v[156:159], v[214:217], v[26:29]
	v_mfma_f32_16x16x32_bf16 v[14:17], v[148:151], v[222:225], v[14:17]
	v_mfma_f32_16x16x32_bf16 v[10:13], v[156:159], v[222:225], v[10:13]
	v_mfma_f32_16x16x32_bf16 v[54:57], v[166:169], v[194:197], v[54:57]
	v_mfma_f32_16x16x32_bf16 v[50:53], v[174:177], v[194:197], v[50:53]
	v_mfma_f32_16x16x32_bf16 v[38:41], v[166:169], v[202:205], v[38:41]
	v_mfma_f32_16x16x32_bf16 v[34:37], v[174:177], v[202:205], v[34:37]
	v_mfma_f32_16x16x32_bf16 v[22:25], v[166:169], v[210:213], v[22:25]
	v_mfma_f32_16x16x32_bf16 v[18:21], v[174:177], v[210:213], v[18:21]
	v_mfma_f32_16x16x32_bf16 v[6:9], v[166:169], v[218:221], v[6:9]
	v_mfma_f32_16x16x32_bf16 v[2:5], v[174:177], v[218:221], v[2:5]
	v_mfma_f32_16x16x32_bf16 v[54:57], v[170:173], v[198:201], v[54:57]
	v_mfma_f32_16x16x32_bf16 v[50:53], v[178:181], v[198:201], v[50:53]
	v_mfma_f32_16x16x32_bf16 v[38:41], v[170:173], v[206:209], v[38:41]
	v_mfma_f32_16x16x32_bf16 v[34:37], v[178:181], v[206:209], v[34:37]
	v_mfma_f32_16x16x32_bf16 v[22:25], v[170:173], v[214:217], v[22:25]
	v_mfma_f32_16x16x32_bf16 v[18:21], v[178:181], v[214:217], v[18:21]
	v_mfma_f32_16x16x32_bf16 v[6:9], v[170:173], v[222:225], v[6:9]
	v_mfma_f32_16x16x32_bf16 v[2:5], v[178:181], v[222:225], v[2:5]
	s_barrier
	s_setprio 0
	s_add_i32 s50, 0, 0x18000
	s_add_i32 s51, 0, 0x1c000
	v_add_u32_e32 v156, s50, v145
	v_add_u32_e32 v178, s51, v145
	ds_read_b128 v[140:143], v156
	ds_read_b128 v[148:151], v156 offset:1024
	ds_read_b128 v[152:155], v156 offset:2048
	ds_read_b128 v[156:159], v156 offset:3072
	ds_read_b128 v[166:169], v178
	ds_read_b128 v[170:173], v178 offset:1024
	ds_read_b128 v[174:177], v178 offset:2048
	ds_read_b128 v[178:181], v178 offset:3072
	s_add_u32 s34, s34, 0x80000
	s_addc_u32 s35, s35, 0
	s_mov_b32 m0, s36
	v_lshl_add_u64 v[234:235], s[34:35], 0, v[134:135]
	ds_read_b128 v[194:197], v147 offset:32768
	ds_read_b128 v[198:201], v147 offset:33792
	ds_read_b128 v[202:205], v147 offset:34816
	ds_read_b128 v[206:209], v147 offset:35840
	ds_read_b128 v[210:213], v147 offset:36864
	ds_read_b128 v[214:217], v147 offset:37888
	ds_read_b128 v[218:221], v147 offset:38912
	ds_read_b128 v[222:225], v147 offset:39936
	global_load_lds_dwordx4 v[234:235], off
	v_lshl_add_u64 v[234:235], s[34:35], 0, v[132:133]
	s_mov_b32 m0, s37
	s_nop 0
	global_load_lds_dwordx4 v[234:235], off
	s_waitcnt vmcnt(8)
	s_waitcnt lgkmcnt(0)
	s_setprio 1
	s_barrier
	v_mfma_f32_16x16x32_bf16 v[126:129], v[140:143], v[194:197], v[126:129]
	v_mfma_f32_16x16x32_bf16 v[122:125], v[152:155], v[194:197], v[122:125]
	v_mfma_f32_16x16x32_bf16 v[110:113], v[140:143], v[202:205], v[110:113]
	v_mfma_f32_16x16x32_bf16 v[106:109], v[152:155], v[202:205], v[106:109]
	v_mfma_f32_16x16x32_bf16 v[94:97], v[140:143], v[210:213], v[94:97]
	v_mfma_f32_16x16x32_bf16 v[90:93], v[152:155], v[210:213], v[90:93]
	v_mfma_f32_16x16x32_bf16 v[78:81], v[140:143], v[218:221], v[78:81]
	v_mfma_f32_16x16x32_bf16 v[74:77], v[152:155], v[218:221], v[74:77]
	v_mfma_f32_16x16x32_bf16 v[126:129], v[148:151], v[198:201], v[126:129]
	v_mfma_f32_16x16x32_bf16 v[122:125], v[156:159], v[198:201], v[122:125]
	v_mfma_f32_16x16x32_bf16 v[110:113], v[148:151], v[206:209], v[110:113]
	v_mfma_f32_16x16x32_bf16 v[106:109], v[156:159], v[206:209], v[106:109]
	v_mfma_f32_16x16x32_bf16 v[94:97], v[148:151], v[214:217], v[94:97]
	v_mfma_f32_16x16x32_bf16 v[90:93], v[156:159], v[214:217], v[90:93]
	v_mfma_f32_16x16x32_bf16 v[78:81], v[148:151], v[222:225], v[78:81]
	v_mfma_f32_16x16x32_bf16 v[74:77], v[156:159], v[222:225], v[74:77]
	v_mfma_f32_16x16x32_bf16 v[118:121], v[166:169], v[194:197], v[118:121]
	v_mfma_f32_16x16x32_bf16 v[114:117], v[174:177], v[194:197], v[114:117]
	v_mfma_f32_16x16x32_bf16 v[102:105], v[166:169], v[202:205], v[102:105]
	v_mfma_f32_16x16x32_bf16 v[98:101], v[174:177], v[202:205], v[98:101]
	v_mfma_f32_16x16x32_bf16 v[86:89], v[166:169], v[210:213], v[86:89]
	v_mfma_f32_16x16x32_bf16 v[82:85], v[174:177], v[210:213], v[82:85]
	v_mfma_f32_16x16x32_bf16 v[70:73], v[166:169], v[218:221], v[70:73]
	v_mfma_f32_16x16x32_bf16 v[66:69], v[174:177], v[218:221], v[66:69]
	v_mfma_f32_16x16x32_bf16 v[118:121], v[170:173], v[198:201], v[118:121]
	v_mfma_f32_16x16x32_bf16 v[114:117], v[178:181], v[198:201], v[114:117]
	v_mfma_f32_16x16x32_bf16 v[102:105], v[170:173], v[206:209], v[102:105]
	v_mfma_f32_16x16x32_bf16 v[98:101], v[178:181], v[206:209], v[98:101]
	v_mfma_f32_16x16x32_bf16 v[86:89], v[170:173], v[214:217], v[86:89]
	v_mfma_f32_16x16x32_bf16 v[82:85], v[178:181], v[214:217], v[82:85]
	v_mfma_f32_16x16x32_bf16 v[70:73], v[170:173], v[222:225], v[70:73]
	v_mfma_f32_16x16x32_bf16 v[66:69], v[178:181], v[222:225], v[66:69]
	s_barrier
; #define PG8_STAGE(bufoff, gbase, voff) do { _Pragma("unroll") for (int _i = 0; _i < 2; ++_i) \
;         __builtin_amdgcn_global_load_lds((const unsigned*)((const char*)(gbase) + (voff)[_i]), (LAS unsigned*)(lds + (bufoff) + ldsw + _i * 8192), 16, 0, 0); } while (0)
; #define PG8_LDA(dst, b, h) do { _Pragma("unroll") for (int m = 0; m < 4; ++m) _Pragma("unroll") for (int k = 0; k < 2; ++k) dst[m][k] = *(const LAS bf16x8*)(lds + PG8_SA(b, h) + aoff + m * 2048 + k * 1024); } while (0)
; #define PG8_MMA(ai, bj, At, Bt) do { __builtin_amdgcn_s_setprio(1); _Pragma("unroll") for (int m = 0; m < 4; ++m) _Pragma("unroll") for (int n = 0; n < 2; ++n) _Pragma("unroll") for (int k = 0; k < 2; ++k) \
;         acc[ai][bj][m][n] = __builtin_amdgcn_mfma_f32_16x16x32_bf16(Bt[n][k], At[m][k], acc[ai][bj][m][n], 0, 0, 0); __builtin_amdgcn_s_setprio(0); } while (0)
; #define PG8_WAIT_V(n) asm volatile("s_waitcnt vmcnt(" #n ")" ::: "memory")
; #define PG8_WAIT_L(n) asm volatile("s_waitcnt lgkmcnt(" #n ")" ::: "memory")
; #define PG8_BAR __builtin_amdgcn_s_barrier()
; #define PG8_SCHED __builtin_amdgcn_sched_barrier(0)
; template <class Epi>
; __device__ __forceinline__ void gemm_phase(LAS unsigned char* lds, const Gemm g, const StaticOrder& S, const Epi& E) {
;     ...
;             PG8_LDA(At, 1, 1); PG8_STAGE(PG8_SB(1, 0), b3, voffB); PG8_STAGE(PG8_SB(1, 1), b3 + hstepB, voffB); PG8_STAGE(PG8_SA(1, 0), a3, voffA);
;             PG8_WAIT_V(8); PG8_WAIT_L(0); PG8_BAR; PG8_MMA(1, 0, At, B0); PG8_MMA(1, 1, At, B1); PG8_BAR; PG8_SCHED;
;         }
;         if (wr == 0) PG8_BAR;
	s_setprio 0
	s_add_i32 s34, s50, s23
	v_lshl_add_u64 v[160:161], v[160:161], 0, s[76:77]
	s_mov_b32 m0, s34
	ds_read_b128 v[194:197], v147 offset:49152
	ds_read_b128 v[198:201], v147 offset:50176
	ds_read_b128 v[202:205], v147 offset:51200
	ds_read_b128 v[206:209], v147 offset:52224
	ds_read_b128 v[210:213], v147 offset:53248
	ds_read_b128 v[214:217], v147 offset:54272
	ds_read_b128 v[218:221], v147 offset:55296
	ds_read_b128 v[222:225], v147 offset:56320
	global_load_lds_dwordx4 v[160:161], off
	s_add_i32 m0, s34, 0x2000
	s_add_u32 s26, s26, 0x80080
	v_lshl_add_u64 v[160:161], v[182:183], 0, s[76:77]
	s_addc_u32 s27, s27, 0
	s_add_i32 s34, s51, s23
	global_load_lds_dwordx4 v[160:161], off
	v_lshl_add_u64 v[160:161], s[26:27], 0, v[0:1]
	s_mov_b32 m0, s34
	s_nop 0
	global_load_lds_dwordx4 v[160:161], off
	v_lshl_add_u64 v[160:161], s[26:27], 0, v[130:131]
	s_add_i32 m0, s34, 0x2000
	s_nop 0
	global_load_lds_dwordx4 v[160:161], off
	v_lshl_add_u64 v[160:161], v[226:227], 0, s[76:77]
	s_mov_b32 m0, s38
	s_nop 0
	global_load_lds_dwordx4 v[160:161], off
	v_lshl_add_u64 v[160:161], v[228:229], 0, s[76:77]
	s_mov_b32 m0, s39
	s_nop 0
	global_load_lds_dwordx4 v[160:161], off
	s_waitcnt vmcnt(8)
	s_waitcnt lgkmcnt(0)
	s_setprio 1
	s_barrier
	v_mfma_f32_16x16x32_bf16 v[62:65], v[140:143], v[194:197], v[62:65]
	v_mfma_f32_16x16x32_bf16 v[58:61], v[152:155], v[194:197], v[58:61]
	v_mfma_f32_16x16x32_bf16 v[46:49], v[140:143], v[202:205], v[46:49]
	v_mfma_f32_16x16x32_bf16 v[42:45], v[152:155], v[202:205], v[42:45]
	v_mfma_f32_16x16x32_bf16 v[30:33], v[140:143], v[210:213], v[30:33]
	v_mfma_f32_16x16x32_bf16 v[26:29], v[152:155], v[210:213], v[26:29]
	v_mfma_f32_16x16x32_bf16 v[14:17], v[140:143], v[218:221], v[14:17]
	v_mfma_f32_16x16x32_bf16 v[10:13], v[152:155], v[218:221], v[10:13]
	v_mfma_f32_16x16x32_bf16 v[62:65], v[148:151], v[198:201], v[62:65]
	v_mfma_f32_16x16x32_bf16 v[58:61], v[156:159], v[198:201], v[58:61]
	v_mfma_f32_16x16x32_bf16 v[46:49], v[148:151], v[206:209], v[46:49]
	v_mfma_f32_16x16x32_bf16 v[42:45], v[156:159], v[206:209], v[42:45]
	v_mfma_f32_16x16x32_bf16 v[30:33], v[148:151], v[214:217], v[30:33]
	v_mfma_f32_16x16x32_bf16 v[26:29], v[156:159], v[214:217], v[26:29]
	v_mfma_f32_16x16x32_bf16 v[14:17], v[148:151], v[222:225], v[14:17]
	v_mfma_f32_16x16x32_bf16 v[10:13], v[156:159], v[222:225], v[10:13]
	v_mfma_f32_16x16x32_bf16 v[54:57], v[166:169], v[194:197], v[54:57]
	v_mfma_f32_16x16x32_bf16 v[50:53], v[174:177], v[194:197], v[50:53]
	v_mfma_f32_16x16x32_bf16 v[38:41], v[166:169], v[202:205], v[38:41]
	v_mfma_f32_16x16x32_bf16 v[34:37], v[174:177], v[202:205], v[34:37]
	v_mfma_f32_16x16x32_bf16 v[22:25], v[166:169], v[210:213], v[22:25]
	v_mfma_f32_16x16x32_bf16 v[18:21], v[174:177], v[210:213], v[18:21]
	v_mfma_f32_16x16x32_bf16 v[6:9], v[166:169], v[218:221], v[6:9]
	v_mfma_f32_16x16x32_bf16 v[2:5], v[174:177], v[218:221], v[2:5]
	v_mfma_f32_16x16x32_bf16 v[54:57], v[170:173], v[198:201], v[54:57]
	v_mfma_f32_16x16x32_bf16 v[50:53], v[178:181], v[198:201], v[50:53]
	v_mfma_f32_16x16x32_bf16 v[38:41], v[170:173], v[206:209], v[38:41]
	v_mfma_f32_16x16x32_bf16 v[34:37], v[178:181], v[206:209], v[34:37]
	v_mfma_f32_16x16x32_bf16 v[22:25], v[170:173], v[214:217], v[22:25]
	v_mfma_f32_16x16x32_bf16 v[18:21], v[178:181], v[214:217], v[18:21]
	v_mfma_f32_16x16x32_bf16 v[6:9], v[170:173], v[222:225], v[6:9]
	v_mfma_f32_16x16x32_bf16 v[2:5], v[178:181], v[222:225], v[2:5]
	s_barrier
	s_setprio 0
	s_add_i32 s49, s49, 2
	s_add_u32 s24, s24, 0x100
	s_addc_u32 s25, s25, 0
	s_add_u32 s47, s47, 0x100
	s_addc_u32 s48, s48, 0
	s_cmp_gt_u32 s49, 29
	s_cbranch_scc0 .LBB0_295
	s_and_b64 vcc, exec, s[8:9]
	s_cbranch_vccz .LBB0_298
	s_barrier
